# hoisted P8 epilogue rowsq loads + hand-scheduled MLA compute block (deeper LDS prefetch)
# speedup vs baseline: 1.0059x; 1.0059x over previous
; #define LAS __attribute__((address_space(3)))
; DI float xhalf_max(float v) { unsigned a = __builtin_bit_cast(unsigned, v), b = a; swap32(a, b); return fmaxf(__builtin_bit_cast(float, a), __builtin_bit_cast(float, b)); }
; DI float fexp2(float x) { return __builtin_amdgcn_exp2f(x); }
; #define MFMA32(a, b, c) __builtin_amdgcn_mfma_f32_32x32x16_bf16((a), (b), (c), 0, 0, 0)
; DI void mla_unit(const Params& p, LAS unsigned char* lds, int b, int h, int qb, int tid) {
;     ...
;                 const int kbase = kt * 64 + 32 * sub;
;                 f32x16 s;
; #pragma unroll
;                 for (int i = 0; i < 16; ++i) s[i] = 0.f;
; #pragma unroll
;                 for (int st = 0; st < 12; ++st) {
;                     const bf16x8 a = *(LAS const bf16x8*)(buf + (32 * sub + c) * 400 + st * 32 + hi * 16);
;                     s = MFMA32(a, qf[st], s);
;                 }
;                 if (kbase + 31 > qw0) {
;                     int dbase = qpos - kbase - 4 * hi;
;                     asm volatile("" : "+v"(dbase));
; #pragma unroll
;                     for (int i = 0; i < 16; ++i) if ((dbase - ((i & 3) + 8 * (i >> 2))) < 0) s[i] = -1e30f;
;                 }
;                 float mx = max16(s);
;                 mx = xhalf_max(mx);
;                 const float mn = (mx > m + 8.f) ? mx : m, alpha = fexp2(m - mn); m = mn; l *= alpha;
;                 if (__any(alpha != 1.f)) {
; #pragma unroll
;                     for (int db = 0; db < 4; ++db) o[db] = o[db] * alpha;
;                 }
;     ...
;                 for (int db = 0; db < 4; ++db) {
;                     LAS const unsigned char* ap = buf + 25600 + (32 * db + c) * 136 + (32 * sub + 4 * hi) * 2;
;                     const bf16x8 v0 = cat4(*(LAS const bf16x4*)(ap), *(LAS const bf16x4*)(ap + 16));
;                     const bf16x8 v1 = cat4(*(LAS const bf16x4*)(ap + 32), *(LAS const bf16x4*)(ap + 48));
.LBB0_627:
	s_bitcmp1_b32 s2, 0
	s_cselect_b32 s2, 0xa800, 0
	s_add_i32 s46, s2, 0
	v_add3_u32 v168, v148, v178, s46
	v_add3_u32 v181, v153, v177, s46
	v_add_u32_e32 v242, 0x6000, v181
	v_add_u32_e32 v243, 0x7000, v181
	v_add_u32_e32 v244, 0x8000, v181
	v_add_u32_e32 v245, 0x9000, v181
	ds_read_b128 v[182:185], v168
	ds_read_b128 v[186:189], v168 offset:32
	ds_read_b128 v[190:193], v168 offset:64
	ds_read_b128 v[194:197], v168 offset:96
	ds_read_b128 v[198:201], v168 offset:128
	ds_read_b128 v[202:205], v168 offset:160
	s_waitcnt lgkmcnt(5)
	v_mfma_f32_32x32x16_bf16 v[64:79], v[182:185], v[80:83], 0
	ds_read_b128 v[182:185], v168 offset:192
	s_waitcnt lgkmcnt(5)
	v_mfma_f32_32x32x16_bf16 v[64:79], v[186:189], v[84:87], v[64:79]
	ds_read_b128 v[186:189], v168 offset:224
	s_waitcnt lgkmcnt(5)
	v_mfma_f32_32x32x16_bf16 v[64:79], v[190:193], v[88:91], v[64:79]
	ds_read_b128 v[190:193], v168 offset:256
	s_waitcnt lgkmcnt(5)
	v_mfma_f32_32x32x16_bf16 v[64:79], v[194:197], v[92:95], v[64:79]
	ds_read_b128 v[194:197], v168 offset:288
	s_waitcnt lgkmcnt(5)
	v_mfma_f32_32x32x16_bf16 v[64:79], v[198:201], v[96:99], v[64:79]
	ds_read_b128 v[198:201], v168 offset:320
	s_waitcnt lgkmcnt(5)
	v_mfma_f32_32x32x16_bf16 v[64:79], v[202:205], v[100:103], v[64:79]
	ds_read_b128 v[202:205], v168 offset:352
	s_waitcnt lgkmcnt(5)
	v_mfma_f32_32x32x16_bf16 v[64:79], v[182:185], v[104:107], v[64:79]
	ds_read2_b64 v[206:209], v242 offset0:128 offset1:130
	s_waitcnt lgkmcnt(5)
	v_mfma_f32_32x32x16_bf16 v[64:79], v[186:189], v[108:111], v[64:79]
	ds_read2_b64 v[210:213], v243 offset0:160 offset1:162
	s_waitcnt lgkmcnt(5)
	v_mfma_f32_32x32x16_bf16 v[64:79], v[190:193], v[112:115], v[64:79]
	ds_read2_b64 v[214:217], v244 offset0:192 offset1:194
	s_waitcnt lgkmcnt(5)
	v_mfma_f32_32x32x16_bf16 v[64:79], v[194:197], v[116:119], v[64:79]
	ds_read2_b64 v[218:221], v245 offset0:224 offset1:226
	s_waitcnt lgkmcnt(5)
	v_mfma_f32_32x32x16_bf16 v[64:79], v[198:201], v[120:123], v[64:79]
	ds_read2_b64 v[222:225], v242 offset0:132 offset1:134
	s_waitcnt lgkmcnt(5)
	v_mfma_f32_32x32x16_bf16 v[64:79], v[202:205], v[124:127], v[64:79]
	ds_read2_b64 v[226:229], v243 offset0:164 offset1:166
	ds_read2_b64 v[230:233], v244 offset0:196 offset1:198
	ds_read2_b64 v[236:239], v245 offset0:228 offset1:230
	s_add_i32 s2, s80, 31
	s_cmp_le_i32 s2, s58
	s_nop 5
	s_cbranch_scc1 .Lmla_nomask_0
	v_mov_b32_e32 v240, v179
	s_nop 0
	v_cmp_gt_i32_e64 s[30:31], 26, v240
	v_cmp_gt_i32_e64 s[34:35], 27, v240
	v_cmp_gt_i32_e64 s[28:29], 25, v240
	s_and_b64 s[30:31], s[34:35], s[30:31]
	v_cmp_gt_i32_e64 s[26:27], 24, v240
	s_and_b64 s[28:29], s[30:31], s[28:29]
	v_cmp_gt_i32_e64 s[24:25], 19, v240
	s_and_b64 s[26:27], s[28:29], s[26:27]
	v_cmp_gt_i32_e64 s[22:23], 18, v240
	s_and_b64 s[24:25], s[26:27], s[24:25]
	v_cmp_gt_i32_e64 s[20:21], 17, v240
	s_and_b64 s[22:23], s[24:25], s[22:23]
	v_cmp_gt_i32_e64 s[18:19], 16, v240
	s_and_b64 s[20:21], s[22:23], s[20:21]
	v_cmp_gt_i32_e64 s[16:17], 11, v240
	s_and_b64 s[18:19], s[20:21], s[18:19]
	v_cmp_gt_i32_e64 s[14:15], 10, v240
	s_and_b64 s[16:17], s[18:19], s[16:17]
	v_cmp_gt_i32_e64 s[10:11], 9, v240
	s_and_b64 s[14:15], s[16:17], s[14:15]
	v_cmp_gt_i32_e64 s[8:9], 8, v240
	s_and_b64 s[10:11], s[14:15], s[10:11]
	v_cmp_gt_i32_e64 s[6:7], 3, v240
	s_and_b64 s[8:9], s[10:11], s[8:9]
	v_cmp_gt_i32_e64 s[4:5], 2, v240
	s_and_b64 s[6:7], s[8:9], s[6:7]
	v_cmp_gt_i32_e64 s[2:3], 1, v240
	s_and_b64 s[4:5], s[6:7], s[4:5]
	v_cmp_gt_i32_e32 vcc, 0, v240
	s_and_b64 s[2:3], s[4:5], s[2:3]
	s_and_b64 vcc, s[2:3], vcc
	s_nop 1
	v_cndmask_b32_e64 v79, v79, v170, s[34:35]
	v_cndmask_b32_e64 v78, v78, v170, s[30:31]
	v_cndmask_b32_e64 v77, v77, v170, s[28:29]
	v_cndmask_b32_e64 v76, v76, v170, s[26:27]
	v_cndmask_b32_e64 v75, v75, v170, s[24:25]
	v_cndmask_b32_e64 v74, v74, v170, s[22:23]
	v_cndmask_b32_e64 v73, v73, v170, s[20:21]
	v_cndmask_b32_e64 v72, v72, v170, s[18:19]
	v_cndmask_b32_e64 v71, v71, v170, s[16:17]
	v_cndmask_b32_e64 v70, v70, v170, s[14:15]
	v_cndmask_b32_e64 v69, v69, v170, s[10:11]
	v_cndmask_b32_e64 v68, v68, v170, s[8:9]
	v_cndmask_b32_e64 v67, v67, v170, s[6:7]
	v_cndmask_b32_e64 v66, v66, v170, s[4:5]
	v_cndmask_b32_e64 v65, v65, v170, s[2:3]
	v_cndmask_b32_e32 v64, v64, v170, vcc
.Lmla_nomask_0:
	v_max3_f32 v240, v64, v65, v66
	v_max3_f32 v241, v67, v68, v69
	v_max3_f32 v246, v70, v71, v72
	v_max3_f32 v247, v73, v74, v75
	v_max3_f32 v240, v240, v76, v77
	v_max3_f32 v241, v241, v78, v79
	v_max3_f32 v240, v240, v241, v246
	v_max3_f32 v240, v240, v247, v247
	v_mov_b32_e32 v241, v240
	s_nop 1
	v_permlane32_swap_b32_e32 v240, v241
	s_nop 0
	v_max_f32_e32 v240, v240, v241
	v_add_f32_e32 v241, 0x41000000, v180
	v_cmp_gt_f32_e32 vcc, v240, v241
	s_nop 1
	v_cndmask_b32_e32 v241, v180, v240, vcc
	v_sub_f32_e32 v166, v180, v241
	v_mov_b32_e32 v180, v241
	v_exp_f32_e32 v166, v166
	s_nop 0
	v_cmp_neq_f32_e32 vcc, 1.0, v166
	s_cbranch_vccz .Lmla_norescale_0
	v_pk_mul_f32 v[62:63], v[62:63], v[166:167] op_sel_hi:[1,0]
	v_pk_mul_f32 v[60:61], v[60:61], v[166:167] op_sel_hi:[1,0]
	v_pk_mul_f32 v[58:59], v[58:59], v[166:167] op_sel_hi:[1,0]
	v_pk_mul_f32 v[56:57], v[56:57], v[166:167] op_sel_hi:[1,0]
	v_pk_mul_f32 v[54:55], v[54:55], v[166:167] op_sel_hi:[1,0]
	v_pk_mul_f32 v[52:53], v[52:53], v[166:167] op_sel_hi:[1,0]
	v_pk_mul_f32 v[50:51], v[50:51], v[166:167] op_sel_hi:[1,0]
	v_pk_mul_f32 v[48:49], v[48:49], v[166:167] op_sel_hi:[1,0]
	v_pk_mul_f32 v[46:47], v[46:47], v[166:167] op_sel_hi:[1,0]
	v_pk_mul_f32 v[44:45], v[44:45], v[166:167] op_sel_hi:[1,0]
	v_pk_mul_f32 v[42:43], v[42:43], v[166:167] op_sel_hi:[1,0]
	v_pk_mul_f32 v[40:41], v[40:41], v[166:167] op_sel_hi:[1,0]
	v_pk_mul_f32 v[38:39], v[38:39], v[166:167] op_sel_hi:[1,0]
	v_pk_mul_f32 v[36:37], v[36:37], v[166:167] op_sel_hi:[1,0]
	v_pk_mul_f32 v[34:35], v[34:35], v[166:167] op_sel_hi:[1,0]
	v_pk_mul_f32 v[32:33], v[32:33], v[166:167] op_sel_hi:[1,0]
	v_pk_mul_f32 v[30:31], v[30:31], v[166:167] op_sel_hi:[1,0]
	v_pk_mul_f32 v[28:29], v[28:29], v[166:167] op_sel_hi:[1,0]
	v_pk_mul_f32 v[26:27], v[26:27], v[166:167] op_sel_hi:[1,0]
	v_pk_mul_f32 v[24:25], v[24:25], v[166:167] op_sel_hi:[1,0]
	v_pk_mul_f32 v[22:23], v[22:23], v[166:167] op_sel_hi:[1,0]
	v_pk_mul_f32 v[20:21], v[20:21], v[166:167] op_sel_hi:[1,0]
	v_pk_mul_f32 v[18:19], v[18:19], v[166:167] op_sel_hi:[1,0]
	v_pk_mul_f32 v[16:17], v[16:17], v[166:167] op_sel_hi:[1,0]
	v_pk_mul_f32 v[14:15], v[14:15], v[166:167] op_sel_hi:[1,0]
	v_pk_mul_f32 v[12:13], v[12:13], v[166:167] op_sel_hi:[1,0]
	v_pk_mul_f32 v[10:11], v[10:11], v[166:167] op_sel_hi:[1,0]
	v_pk_mul_f32 v[8:9], v[8:9], v[166:167] op_sel_hi:[1,0]
	v_pk_mul_f32 v[6:7], v[6:7], v[166:167] op_sel_hi:[1,0]
	v_pk_mul_f32 v[4:5], v[4:5], v[166:167] op_sel_hi:[1,0]
	v_pk_mul_f32 v[2:3], v[2:3], v[166:167] op_sel_hi:[1,0]
	v_pk_mul_f32 v[0:1], v[0:1], v[166:167] op_sel_hi:[1,0]
; #define LAS __attribute__((address_space(3)))
; DI float fexp2(float x) { return __builtin_amdgcn_exp2f(x); }
; #define MFMA32(a, b, c) __builtin_amdgcn_mfma_f32_32x32x16_bf16((a), (b), (c), 0, 0, 0)
; DI void mla_unit(const Params& p, LAS unsigned char* lds, int b, int h, int qb, int tid) {
;     ...
;                 const int kbase = kt * 64 + 32 * sub;
;                 f32x16 s;
; #pragma unroll
;                 for (int i = 0; i < 16; ++i) s[i] = 0.f;
; #pragma unroll
;                 for (int st = 0; st < 12; ++st) {
;                     const bf16x8 a = *(LAS const bf16x8*)(buf + (32 * sub + c) * 400 + st * 32 + hi * 16);
;                     s = MFMA32(a, qf[st], s);
;                 }
;                 if (kbase + 31 > qw0) {
;                     int dbase = qpos - kbase - 4 * hi;
;                     asm volatile("" : "+v"(dbase));
; #pragma unroll
;                     for (int i = 0; i < 16; ++i) if ((dbase - ((i & 3) + 8 * (i >> 2))) < 0) s[i] = -1e30f;
;     ...
;                 float ps = 0.f;
; #pragma unroll
;                 for (int i = 0; i < 16; ++i) { const float pv = fexp2(s[i] - m); s[i] = pv; ps += pv; }
;                 l += ps;
;                 const bf16x8 pb0 = packp(s, 0), pb1 = packp(s, 1);
; #pragma unroll
;                 for (int db = 0; db < 4; ++db) {
;                     LAS const unsigned char* ap = buf + 25600 + (32 * db + c) * 136 + (32 * sub + 4 * hi) * 2;
;                     const bf16x8 v0 = cat4(*(LAS const bf16x4*)(ap), *(LAS const bf16x4*)(ap + 16));
;                     const bf16x8 v1 = cat4(*(LAS const bf16x4*)(ap + 32), *(LAS const bf16x4*)(ap + 48));
;                     o[db] = MFMA32(v0, pb0, o[db]); o[db] = MFMA32(v1, pb1, o[db]);
;                 }
.Lmla_norescale_0:
	v_sub_f32_e32 v64, v64, v180
	v_sub_f32_e32 v65, v65, v180
	v_sub_f32_e32 v66, v66, v180
	v_sub_f32_e32 v67, v67, v180
	v_sub_f32_e32 v68, v68, v180
	v_sub_f32_e32 v69, v69, v180
	v_sub_f32_e32 v70, v70, v180
	v_sub_f32_e32 v71, v71, v180
	v_exp_f32_e32 v64, v64
	v_exp_f32_e32 v65, v65
	v_exp_f32_e32 v66, v66
	v_exp_f32_e32 v67, v67
	v_exp_f32_e32 v68, v68
	v_exp_f32_e32 v69, v69
	v_exp_f32_e32 v70, v70
	v_exp_f32_e32 v71, v71
	v_sub_f32_e32 v72, v72, v180
	v_sub_f32_e32 v73, v73, v180
	v_sub_f32_e32 v74, v74, v180
	v_sub_f32_e32 v75, v75, v180
	v_cvt_pk_bf16_f32 v198, v64, v65
	v_cvt_pk_bf16_f32 v199, v66, v67
	v_cvt_pk_bf16_f32 v200, v68, v69
	v_cvt_pk_bf16_f32 v201, v70, v71
	v_sub_f32_e32 v76, v76, v180
	v_sub_f32_e32 v77, v77, v180
	v_sub_f32_e32 v78, v78, v180
	v_sub_f32_e32 v79, v79, v180
	s_waitcnt lgkmcnt(7)
	v_mfma_f32_32x32x16_bf16 v[48:63], v[206:209], v[198:201], v[48:63]
	v_exp_f32_e32 v72, v72
	v_exp_f32_e32 v73, v73
	ds_read_b128 v[182:185], v168 offset:12800
	v_add_f32_e32 v240, v64, v65
	v_add_f32_e32 v241, v66, v67
	s_waitcnt lgkmcnt(7)
	v_mfma_f32_32x32x16_bf16 v[32:47], v[210:213], v[198:201], v[32:47]
	v_exp_f32_e32 v74, v74
	v_exp_f32_e32 v75, v75
	ds_read_b128 v[186:189], v168 offset:12832
	v_add_f32_e32 v246, v68, v69
	v_add_f32_e32 v247, v70, v71
	s_waitcnt lgkmcnt(7)
	v_mfma_f32_32x32x16_bf16 v[16:31], v[214:217], v[198:201], v[16:31]
	v_exp_f32_e32 v76, v76
	v_exp_f32_e32 v77, v77
	ds_read_b128 v[190:193], v168 offset:12864
	s_waitcnt lgkmcnt(7)
	v_mfma_f32_32x32x16_bf16 v[0:15], v[218:221], v[198:201], v[0:15]
	v_exp_f32_e32 v78, v78
	v_exp_f32_e32 v79, v79
	ds_read_b128 v[194:197], v168 offset:12896
	v_cvt_pk_bf16_f32 v202, v72, v73
	v_cvt_pk_bf16_f32 v203, v74, v75
	v_cvt_pk_bf16_f32 v204, v76, v77
	v_cvt_pk_bf16_f32 v205, v78, v79
	v_add_f32_e32 v240, v240, v72
	v_add_f32_e32 v241, v241, v73
	s_waitcnt lgkmcnt(7)
	v_mfma_f32_32x32x16_bf16 v[48:63], v[222:225], v[202:205], v[48:63]
	v_add_f32_e32 v246, v246, v74
	v_add_f32_e32 v247, v247, v75
	v_add_f32_e32 v240, v240, v76
	s_waitcnt lgkmcnt(6)
	v_mfma_f32_32x32x16_bf16 v[32:47], v[226:229], v[202:205], v[32:47]
	v_add_f32_e32 v241, v241, v77
	v_add_f32_e32 v246, v246, v78
	v_add_f32_e32 v247, v247, v79
	s_waitcnt lgkmcnt(5)
	v_mfma_f32_32x32x16_bf16 v[16:31], v[230:233], v[202:205], v[16:31]
	v_add_f32_e32 v240, v240, v241
	v_add_f32_e32 v246, v246, v247
	s_waitcnt lgkmcnt(4)
	v_mfma_f32_32x32x16_bf16 v[0:15], v[236:239], v[202:205], v[0:15]
	v_add_f32_e32 v240, v240, v246
	v_fma_f32 v155, v155, v166, v240
	ds_read_b128 v[198:201], v168 offset:12928
	ds_read_b128 v[202:205], v168 offset:12960
	s_waitcnt lgkmcnt(5)
	v_mfma_f32_32x32x16_bf16 v[64:79], v[182:185], v[80:83], 0
	ds_read_b128 v[182:185], v168 offset:12992
	s_waitcnt lgkmcnt(5)
	v_mfma_f32_32x32x16_bf16 v[64:79], v[186:189], v[84:87], v[64:79]
	ds_read_b128 v[186:189], v168 offset:13024
	s_waitcnt lgkmcnt(5)
	v_mfma_f32_32x32x16_bf16 v[64:79], v[190:193], v[88:91], v[64:79]
	ds_read_b128 v[190:193], v168 offset:13056
	s_waitcnt lgkmcnt(5)
	v_mfma_f32_32x32x16_bf16 v[64:79], v[194:197], v[92:95], v[64:79]
	ds_read_b128 v[194:197], v168 offset:13088
	s_waitcnt lgkmcnt(5)
	v_mfma_f32_32x32x16_bf16 v[64:79], v[198:201], v[96:99], v[64:79]
	ds_read_b128 v[198:201], v168 offset:13120
	s_waitcnt lgkmcnt(5)
	v_mfma_f32_32x32x16_bf16 v[64:79], v[202:205], v[100:103], v[64:79]
	ds_read_b128 v[202:205], v168 offset:13152
	s_waitcnt lgkmcnt(5)
	v_mfma_f32_32x32x16_bf16 v[64:79], v[182:185], v[104:107], v[64:79]
	ds_read2_b64 v[206:209], v242 offset0:136 offset1:138
	s_waitcnt lgkmcnt(5)
	v_mfma_f32_32x32x16_bf16 v[64:79], v[186:189], v[108:111], v[64:79]
	ds_read2_b64 v[210:213], v243 offset0:168 offset1:170
	s_waitcnt lgkmcnt(5)
	v_mfma_f32_32x32x16_bf16 v[64:79], v[190:193], v[112:115], v[64:79]
	ds_read2_b64 v[214:217], v244 offset0:200 offset1:202
	s_waitcnt lgkmcnt(5)
	v_mfma_f32_32x32x16_bf16 v[64:79], v[194:197], v[116:119], v[64:79]
	ds_read2_b64 v[218:221], v245 offset0:232 offset1:234
	s_waitcnt lgkmcnt(5)
	v_mfma_f32_32x32x16_bf16 v[64:79], v[198:201], v[120:123], v[64:79]
	ds_read2_b64 v[222:225], v242 offset0:140 offset1:142
	s_waitcnt lgkmcnt(5)
	v_mfma_f32_32x32x16_bf16 v[64:79], v[202:205], v[124:127], v[64:79]
	ds_read2_b64 v[226:229], v243 offset0:172 offset1:174
	ds_read2_b64 v[230:233], v244 offset0:204 offset1:206
	ds_read2_b64 v[236:239], v245 offset0:236 offset1:238
	s_add_i32 s2, s80, 63
	s_cmp_le_i32 s2, s58
	s_nop 5
	s_cbranch_scc1 .Lmla_nomask_1
	v_subrev_u32_e32 v240, 32, v179
	s_nop 0
	v_cmp_gt_i32_e64 s[30:31], 26, v240
	v_cmp_gt_i32_e64 s[34:35], 27, v240
	v_cmp_gt_i32_e64 s[28:29], 25, v240
	s_and_b64 s[30:31], s[34:35], s[30:31]
	v_cmp_gt_i32_e64 s[26:27], 24, v240
	s_and_b64 s[28:29], s[30:31], s[28:29]
	v_cmp_gt_i32_e64 s[24:25], 19, v240
	s_and_b64 s[26:27], s[28:29], s[26:27]
	v_cmp_gt_i32_e64 s[22:23], 18, v240
	s_and_b64 s[24:25], s[26:27], s[24:25]
	v_cmp_gt_i32_e64 s[20:21], 17, v240
	s_and_b64 s[22:23], s[24:25], s[22:23]
	v_cmp_gt_i32_e64 s[18:19], 16, v240
	s_and_b64 s[20:21], s[22:23], s[20:21]
	v_cmp_gt_i32_e64 s[16:17], 11, v240
	s_and_b64 s[18:19], s[20:21], s[18:19]
	v_cmp_gt_i32_e64 s[14:15], 10, v240
	s_and_b64 s[16:17], s[18:19], s[16:17]
	v_cmp_gt_i32_e64 s[10:11], 9, v240
	s_and_b64 s[14:15], s[16:17], s[14:15]
	v_cmp_gt_i32_e64 s[8:9], 8, v240
	s_and_b64 s[10:11], s[14:15], s[10:11]
	v_cmp_gt_i32_e64 s[6:7], 3, v240
	s_and_b64 s[8:9], s[10:11], s[8:9]
	v_cmp_gt_i32_e64 s[4:5], 2, v240
	s_and_b64 s[6:7], s[8:9], s[6:7]
	v_cmp_gt_i32_e64 s[2:3], 1, v240
	s_and_b64 s[4:5], s[6:7], s[4:5]
	v_cmp_gt_i32_e32 vcc, 0, v240
	s_and_b64 s[2:3], s[4:5], s[2:3]
	s_and_b64 vcc, s[2:3], vcc
	s_nop 1
	v_cndmask_b32_e64 v79, v79, v170, s[34:35]
	v_cndmask_b32_e64 v78, v78, v170, s[30:31]
	v_cndmask_b32_e64 v77, v77, v170, s[28:29]
	v_cndmask_b32_e64 v76, v76, v170, s[26:27]
	v_cndmask_b32_e64 v75, v75, v170, s[24:25]
	v_cndmask_b32_e64 v74, v74, v170, s[22:23]
	v_cndmask_b32_e64 v73, v73, v170, s[20:21]
	v_cndmask_b32_e64 v72, v72, v170, s[18:19]
	v_cndmask_b32_e64 v71, v71, v170, s[16:17]
	v_cndmask_b32_e64 v70, v70, v170, s[14:15]
	v_cndmask_b32_e64 v69, v69, v170, s[10:11]
	v_cndmask_b32_e64 v68, v68, v170, s[8:9]
	v_cndmask_b32_e64 v67, v67, v170, s[6:7]
	v_cndmask_b32_e64 v66, v66, v170, s[4:5]
	v_cndmask_b32_e64 v65, v65, v170, s[2:3]
	v_cndmask_b32_e32 v64, v64, v170, vcc

; #define LAS __attribute__((address_space(3)))
; DI float fexp2(float x) { return __builtin_amdgcn_exp2f(x); }
; #define MFMA32(a, b, c) __builtin_amdgcn_mfma_f32_32x32x16_bf16((a), (b), (c), 0, 0, 0)
; DI void mla_unit(const Params& p, LAS unsigned char* lds, int b, int h, int qb, int tid) {
;     ...
;                 float ps = 0.f;
; #pragma unroll
;                 for (int i = 0; i < 16; ++i) { const float pv = fexp2(s[i] - m); s[i] = pv; ps += pv; }
;                 l += ps;
;                 const bf16x8 pb0 = packp(s, 0), pb1 = packp(s, 1);
; #pragma unroll
;                 for (int db = 0; db < 4; ++db) {
;                     LAS const unsigned char* ap = buf + 25600 + (32 * db + c) * 136 + (32 * sub + 4 * hi) * 2;
;                     const bf16x8 v0 = cat4(*(LAS const bf16x4*)(ap), *(LAS const bf16x4*)(ap + 16));
;                     const bf16x8 v1 = cat4(*(LAS const bf16x4*)(ap + 32), *(LAS const bf16x4*)(ap + 48));
;                     o[db] = MFMA32(v0, pb0, o[db]); o[db] = MFMA32(v1, pb1, o[db]);
;                 }
.Lmla_norescale_1:
	v_sub_f32_e32 v64, v64, v180
	v_sub_f32_e32 v65, v65, v180
	v_sub_f32_e32 v66, v66, v180
	v_sub_f32_e32 v67, v67, v180
	v_sub_f32_e32 v68, v68, v180
	v_sub_f32_e32 v69, v69, v180
	v_sub_f32_e32 v70, v70, v180
	v_sub_f32_e32 v71, v71, v180
	v_exp_f32_e32 v64, v64
	v_exp_f32_e32 v65, v65
	v_exp_f32_e32 v66, v66
	v_exp_f32_e32 v67, v67
	v_exp_f32_e32 v68, v68
	v_exp_f32_e32 v69, v69
	v_exp_f32_e32 v70, v70
	v_exp_f32_e32 v71, v71
	v_sub_f32_e32 v72, v72, v180
	v_sub_f32_e32 v73, v73, v180
	v_sub_f32_e32 v74, v74, v180
	v_sub_f32_e32 v75, v75, v180
	v_cvt_pk_bf16_f32 v198, v64, v65
	v_cvt_pk_bf16_f32 v199, v66, v67
	v_cvt_pk_bf16_f32 v200, v68, v69
	v_cvt_pk_bf16_f32 v201, v70, v71
	v_sub_f32_e32 v76, v76, v180
	v_sub_f32_e32 v77, v77, v180
	v_sub_f32_e32 v78, v78, v180
	v_sub_f32_e32 v79, v79, v180
	s_waitcnt lgkmcnt(7)
	v_mfma_f32_32x32x16_bf16 v[48:63], v[206:209], v[198:201], v[48:63]
	v_exp_f32_e32 v72, v72
	v_exp_f32_e32 v73, v73
	v_add_f32_e32 v240, v64, v65
	v_add_f32_e32 v241, v66, v67
	s_waitcnt lgkmcnt(6)
	v_mfma_f32_32x32x16_bf16 v[32:47], v[210:213], v[198:201], v[32:47]
	v_exp_f32_e32 v74, v74
	v_exp_f32_e32 v75, v75
	v_add_f32_e32 v246, v68, v69
	v_add_f32_e32 v247, v70, v71
	s_waitcnt lgkmcnt(5)
	v_mfma_f32_32x32x16_bf16 v[16:31], v[214:217], v[198:201], v[16:31]
	v_exp_f32_e32 v76, v76
	v_exp_f32_e32 v77, v77
	s_waitcnt lgkmcnt(4)
	v_mfma_f32_32x32x16_bf16 v[0:15], v[218:221], v[198:201], v[0:15]
	v_exp_f32_e32 v78, v78
	v_exp_f32_e32 v79, v79
	v_cvt_pk_bf16_f32 v202, v72, v73
	v_cvt_pk_bf16_f32 v203, v74, v75
	v_cvt_pk_bf16_f32 v204, v76, v77
	v_cvt_pk_bf16_f32 v205, v78, v79
	v_add_f32_e32 v240, v240, v72
	v_add_f32_e32 v241, v241, v73
	s_waitcnt lgkmcnt(3)
	v_mfma_f32_32x32x16_bf16 v[48:63], v[222:225], v[202:205], v[48:63]
	v_add_f32_e32 v246, v246, v74
	v_add_f32_e32 v247, v247, v75
	v_add_f32_e32 v240, v240, v76
	s_waitcnt lgkmcnt(2)
	v_mfma_f32_32x32x16_bf16 v[32:47], v[226:229], v[202:205], v[32:47]
	v_add_f32_e32 v241, v241, v77
	v_add_f32_e32 v246, v246, v78
	v_add_f32_e32 v247, v247, v79
	s_waitcnt lgkmcnt(1)
	v_mfma_f32_32x32x16_bf16 v[16:31], v[230:233], v[202:205], v[16:31]
	v_add_f32_e32 v240, v240, v241
	v_add_f32_e32 v246, v246, v247
	s_waitcnt lgkmcnt(0)
	v_mfma_f32_32x32x16_bf16 v[0:15], v[236:239], v[202:205], v[0:15]
	v_add_f32_e32 v240, v240, v246
	v_fma_f32 v155, v155, v166, v240
	s_andn2_b64 vcc, exec, s[76:77]
	s_cbranch_vccz .LBB0_623
	s_branch .LBB0_624

; DI unsigned pk2(float lo, float hi) { const f32x2 v = {lo, hi}; const hwbf16x2 b = __builtin_convertvector(v, hwbf16x2); return __builtin_bit_cast(unsigned, b); }
; DI float frsq(float x) { return __builtin_amdgcn_rsqf(x); }
; DI float fsilu(float v) { return v * frcp(1.f + __expf(-v)); }
;     DI void operator()(const f32x4 (&acc)[2][2][4][2], const Unit& u, int wr, int wc, int fr, int fq) const {
;         const int row0 = u.pm * BM + wr * 64 + fr, col0 = u.pn * BM + wc * 32 + 8 * fq;
; #pragma unroll
;         for (int ai = 0; ai < 2; ++ai)
; #pragma unroll
;             for (int m = 0; m < 4; ++m) {
;                 const int row = row0 + ai * HALF + m * 16;
;                 float rs = 1.f, rowacc = 0.f;
;                 if (mode == EPI_STORE || mode == EPI_Q) { if (rscale) rs = rscale[row]; }
;                 if (mode == EPI_SWIGLU) rs = frsq(rowsq[row] * (1.0f / DM) + 1e-6f);
; #pragma unroll
;                 for (int bj = 0; bj < 2; ++bj) {
;     ...
;                     } else {
;                         v0 = v0 * rs; v1 = v1 * rs;
;                         u32x2 w; w.x = pk2(fsilu(v0[0]) * v1[0], fsilu(v0[1]) * v1[1]); w.y = pk2(fsilu(v0[2]) * v1[2], fsilu(v0[3]) * v1[3]);
;                         *(u32x2*)(O + (size_t)row * ldc + (col >> 1)) = w;
.LBB0_1023:
	v_lshl_add_u32 v144, s22, 8, v152
	v_ashrrev_i32_e32 v145, 31, v144
	v_lshl_add_u64 v[148:149], v[144:145], 2, s[74:75]
	global_load_dword v236, v[148:149], off
	global_load_dword v237, v[148:149], off offset:64
	global_load_dword v238, v[148:149], off offset:128
	global_load_dword v239, v[148:149], off offset:192
	global_load_dword v240, v[148:149], off offset:512
	global_load_dword v241, v[148:149], off offset:576
	global_load_dword v242, v[148:149], off offset:640
	global_load_dword v243, v[148:149], off offset:704
	v_or_b32_e32 v162, 16, v144
	v_ashrrev_i32_e32 v163, 31, v162
	v_lshl_add_u64 v[170:171], v[162:163], 2, s[74:75]
	v_lshl_or_b32 v150, s40, 8, v154
	v_ashrrev_i32_e32 v150, 1, v150
	v_mov_b64_e32 v[146:147], s[44:45]
	v_ashrrev_i32_e32 v151, 31, v150
	v_mad_i64_i32 v[160:161], s[24:25], v144, s39, v[146:147]
	v_lshlrev_b64 v[150:151], 1, v[150:151]
	v_lshl_add_u64 v[160:161], v[160:161], 0, v[150:151]
	s_andn2_b64 vcc, exec, s[4:5]
	s_mov_b64 s[4:5], -1
	s_waitcnt vmcnt(7)
	v_fmamk_f32 v145, v236, 0x3a000000, v158
	v_rsq_f32_e32 v164, v145
	s_nop 0
	v_pk_mul_f32 v[126:127], v[126:127], v[164:165] op_sel_hi:[1,0]
	v_pk_mul_f32 v[124:125], v[124:125], v[164:165] op_sel_hi:[1,0]
	v_pk_mul_f32 v[122:123], v[122:123], v[164:165] op_sel_hi:[1,0]
	v_pk_mul_f32 v[120:121], v[120:121], v[164:165] op_sel_hi:[1,0]
	v_pk_mul_f32 v[118:119], v[118:119], v[164:165] op_sel_hi:[1,0]
	v_pk_mul_f32 v[116:117], v[116:117], v[164:165] op_sel_hi:[1,0]
	v_pk_mul_f32 v[114:115], v[114:115], v[164:165] op_sel_hi:[1,0]
	v_pk_mul_f32 v[112:113], v[112:113], v[164:165] op_sel_hi:[1,0]
	v_mul_f32_e32 v145, 0xbfb8aa3b, v124
	v_mul_f32_e32 v159, 0xbfb8aa3b, v125
	v_mul_f32_e32 v163, 0xbfb8aa3b, v126
	v_mul_f32_e32 v164, 0xbfb8aa3b, v127
	v_mul_f32_e32 v165, 0xbfb8aa3b, v116
	v_mul_f32_e32 v166, 0xbfb8aa3b, v117
	v_mul_f32_e32 v168, 0xbfb8aa3b, v118
	v_mul_f32_e32 v172, 0xbfb8aa3b, v119
	v_exp_f32_e32 v145, v145
	v_exp_f32_e32 v159, v159
	v_exp_f32_e32 v163, v163
	v_exp_f32_e32 v164, v164
	v_exp_f32_e32 v165, v165
	v_exp_f32_e32 v166, v166
	v_exp_f32_e32 v168, v168
	v_exp_f32_e32 v172, v172
	v_add_f32_e32 v145, 1.0, v145
	v_add_f32_e32 v159, 1.0, v159
	v_add_f32_e32 v163, 1.0, v163
	v_add_f32_e32 v173, 1.0, v164
	v_add_f32_e32 v174, 1.0, v165
	v_add_f32_e32 v166, 1.0, v166
	v_add_f32_e32 v168, 1.0, v168
	v_add_f32_e32 v177, 1.0, v172
	v_rcp_f32_e32 v164, v145
	v_rcp_f32_e32 v165, v159
	v_rcp_f32_e32 v172, v163
	v_rcp_f32_e32 v173, v173
	v_rcp_f32_e32 v174, v174
	v_rcp_f32_e32 v175, v166
	v_rcp_f32_e32 v176, v168
	v_rcp_f32_e32 v177, v177
	v_pk_mul_f32 v[124:125], v[124:125], v[164:165]
	v_pk_mul_f32 v[126:127], v[126:127], v[172:173]
	v_pk_mul_f32 v[116:117], v[116:117], v[174:175]
	v_pk_mul_f32 v[118:119], v[118:119], v[176:177]
	v_pk_mul_f32 v[120:121], v[120:121], v[124:125]
	v_pk_mul_f32 v[122:123], v[122:123], v[126:127]
	v_pk_mul_f32 v[112:113], v[112:113], v[116:117]
	v_pk_mul_f32 v[114:115], v[114:115], v[118:119]
	v_cvt_pk_bf16_f32 v116, v120, v121
	v_cvt_pk_bf16_f32 v117, v122, v123
	v_cvt_pk_bf16_f32 v112, v112, v113
	v_cvt_pk_bf16_f32 v113, v114, v115
	global_store_dwordx2 v[160:161], v[116:117], off
	global_store_dwordx2 v[160:161], v[112:113], off offset:128
	v_or_b32_e32 v112, 32, v144
	v_mad_i64_i32 v[114:115], s[24:25], v162, s39, v[146:147]
	v_lshl_add_u64 v[114:115], v[114:115], 0, v[150:151]
	s_waitcnt vmcnt(8)
	v_fmamk_f32 v113, v237, 0x3a000000, v158
	v_rsq_f32_e32 v116, v113
	v_ashrrev_i32_e32 v113, 31, v112
	v_lshl_add_u64 v[118:119], v[112:113], 2, s[74:75]
	v_pk_mul_f32 v[110:111], v[110:111], v[116:117] op_sel_hi:[1,0]
	v_pk_mul_f32 v[108:109], v[108:109], v[116:117] op_sel_hi:[1,0]
	v_pk_mul_f32 v[106:107], v[106:107], v[116:117] op_sel_hi:[1,0]
	v_pk_mul_f32 v[104:105], v[104:105], v[116:117] op_sel_hi:[1,0]
	v_pk_mul_f32 v[102:103], v[102:103], v[116:117] op_sel_hi:[1,0]
	v_pk_mul_f32 v[100:101], v[100:101], v[116:117] op_sel_hi:[1,0]
	v_pk_mul_f32 v[98:99], v[98:99], v[116:117] op_sel_hi:[1,0]
	v_pk_mul_f32 v[96:97], v[96:97], v[116:117] op_sel_hi:[1,0]
	v_mul_f32_e32 v113, 0xbfb8aa3b, v108
	v_mul_f32_e32 v116, 0xbfb8aa3b, v109
	v_mul_f32_e32 v117, 0xbfb8aa3b, v110
	v_mul_f32_e32 v120, 0xbfb8aa3b, v111
	v_mul_f32_e32 v121, 0xbfb8aa3b, v100
	v_mul_f32_e32 v122, 0xbfb8aa3b, v101
	v_mul_f32_e32 v123, 0xbfb8aa3b, v102
	v_mul_f32_e32 v124, 0xbfb8aa3b, v103
	v_exp_f32_e32 v113, v113
	v_exp_f32_e32 v116, v116
	v_exp_f32_e32 v117, v117
	v_exp_f32_e32 v120, v120
	v_exp_f32_e32 v121, v121
	v_exp_f32_e32 v122, v122
	v_exp_f32_e32 v123, v123
	v_exp_f32_e32 v124, v124
	v_add_f32_e32 v113, 1.0, v113
	v_add_f32_e32 v125, 1.0, v116
	v_add_f32_e32 v126, 1.0, v117
	v_add_f32_e32 v127, 1.0, v120
	v_add_f32_e32 v145, 1.0, v121
	v_add_f32_e32 v159, 1.0, v122
	v_add_f32_e32 v160, 1.0, v123
	v_add_f32_e32 v161, 1.0, v124
	v_rcp_f32_e32 v116, v113
	v_rcp_f32_e32 v117, v125
	v_rcp_f32_e32 v120, v126
	v_rcp_f32_e32 v121, v127
	v_rcp_f32_e32 v122, v145
	v_rcp_f32_e32 v123, v159
	v_rcp_f32_e32 v124, v160
	v_rcp_f32_e32 v125, v161
	v_pk_mul_f32 v[108:109], v[108:109], v[116:117]
	v_pk_mul_f32 v[110:111], v[110:111], v[120:121]
	v_pk_mul_f32 v[100:101], v[100:101], v[122:123]
	v_pk_mul_f32 v[102:103], v[102:103], v[124:125]
	v_pk_mul_f32 v[104:105], v[104:105], v[108:109]
	v_pk_mul_f32 v[106:107], v[106:107], v[110:111]
	v_pk_mul_f32 v[96:97], v[96:97], v[100:101]
	v_pk_mul_f32 v[98:99], v[98:99], v[102:103]
	v_cvt_pk_bf16_f32 v100, v104, v105
	v_cvt_pk_bf16_f32 v101, v106, v107
	v_cvt_pk_bf16_f32 v96, v96, v97
	v_cvt_pk_bf16_f32 v97, v98, v99
	global_store_dwordx2 v[114:115], v[100:101], off
	global_store_dwordx2 v[114:115], v[96:97], off offset:128
	v_or_b32_e32 v96, 48, v144
	v_mad_i64_i32 v[98:99], s[24:25], v112, s39, v[146:147]
	v_lshl_add_u64 v[98:99], v[98:99], 0, v[150:151]
	s_waitcnt vmcnt(9)
; DI unsigned pk2(float lo, float hi) { const f32x2 v = {lo, hi}; const hwbf16x2 b = __builtin_convertvector(v, hwbf16x2); return __builtin_bit_cast(unsigned, b); }
; DI float frsq(float x) { return __builtin_amdgcn_rsqf(x); }
; DI float fsilu(float v) { return v * frcp(1.f + __expf(-v)); }
;     DI void operator()(const f32x4 (&acc)[2][2][4][2], const Unit& u, int wr, int wc, int fr, int fq) const {
;         const int row0 = u.pm * BM + wr * 64 + fr, col0 = u.pn * BM + wc * 32 + 8 * fq;
; #pragma unroll
;         for (int ai = 0; ai < 2; ++ai)
; #pragma unroll
;             for (int m = 0; m < 4; ++m) {
;                 const int row = row0 + ai * HALF + m * 16;
;                 float rs = 1.f, rowacc = 0.f;
;                 if (mode == EPI_STORE || mode == EPI_Q) { if (rscale) rs = rscale[row]; }
;                 if (mode == EPI_SWIGLU) rs = frsq(rowsq[row] * (1.0f / DM) + 1e-6f);
; #pragma unroll
;                 for (int bj = 0; bj < 2; ++bj) {
;     ...
;                     } else {
;                         v0 = v0 * rs; v1 = v1 * rs;
;                         u32x2 w; w.x = pk2(fsilu(v0[0]) * v1[0], fsilu(v0[1]) * v1[1]); w.y = pk2(fsilu(v0[2]) * v1[2], fsilu(v0[3]) * v1[3]);
;                         *(u32x2*)(O + (size_t)row * ldc + (col >> 1)) = w;
	v_fmamk_f32 v97, v238, 0x3a000000, v158
	v_rsq_f32_e32 v100, v97
	v_ashrrev_i32_e32 v97, 31, v96
	v_lshl_add_u64 v[102:103], v[96:97], 2, s[74:75]
	v_pk_mul_f32 v[94:95], v[94:95], v[100:101] op_sel_hi:[1,0]
	v_pk_mul_f32 v[92:93], v[92:93], v[100:101] op_sel_hi:[1,0]
	v_pk_mul_f32 v[90:91], v[90:91], v[100:101] op_sel_hi:[1,0]
	v_pk_mul_f32 v[88:89], v[88:89], v[100:101] op_sel_hi:[1,0]
	v_pk_mul_f32 v[86:87], v[86:87], v[100:101] op_sel_hi:[1,0]
	v_pk_mul_f32 v[84:85], v[84:85], v[100:101] op_sel_hi:[1,0]
	v_pk_mul_f32 v[82:83], v[82:83], v[100:101] op_sel_hi:[1,0]
	v_pk_mul_f32 v[80:81], v[80:81], v[100:101] op_sel_hi:[1,0]
	v_mul_f32_e32 v97, 0xbfb8aa3b, v92
	v_mul_f32_e32 v100, 0xbfb8aa3b, v93
	v_mul_f32_e32 v101, 0xbfb8aa3b, v94
	v_mul_f32_e32 v104, 0xbfb8aa3b, v95
	v_mul_f32_e32 v105, 0xbfb8aa3b, v84
	v_mul_f32_e32 v106, 0xbfb8aa3b, v85
	v_mul_f32_e32 v107, 0xbfb8aa3b, v86
	v_mul_f32_e32 v108, 0xbfb8aa3b, v87
	v_exp_f32_e32 v97, v97
	v_exp_f32_e32 v100, v100
	v_exp_f32_e32 v101, v101
	v_exp_f32_e32 v104, v104
	v_exp_f32_e32 v105, v105
	v_exp_f32_e32 v106, v106
	v_exp_f32_e32 v107, v107
	v_exp_f32_e32 v108, v108
	v_add_f32_e32 v97, 1.0, v97
	v_add_f32_e32 v109, 1.0, v100
	v_add_f32_e32 v110, 1.0, v101
	v_add_f32_e32 v111, 1.0, v104
	v_add_f32_e32 v112, 1.0, v105
	v_add_f32_e32 v113, 1.0, v106
	v_add_f32_e32 v114, 1.0, v107
	v_add_f32_e32 v115, 1.0, v108
	v_rcp_f32_e32 v100, v97
	v_rcp_f32_e32 v101, v109
	v_rcp_f32_e32 v104, v110
	v_rcp_f32_e32 v105, v111
	v_rcp_f32_e32 v106, v112
	v_rcp_f32_e32 v107, v113
	v_rcp_f32_e32 v108, v114
	v_rcp_f32_e32 v109, v115
	v_pk_mul_f32 v[92:93], v[92:93], v[100:101]
	v_pk_mul_f32 v[94:95], v[94:95], v[104:105]
	v_pk_mul_f32 v[84:85], v[84:85], v[106:107]
	v_pk_mul_f32 v[86:87], v[86:87], v[108:109]
	v_pk_mul_f32 v[88:89], v[88:89], v[92:93]
	v_pk_mul_f32 v[90:91], v[90:91], v[94:95]
	v_pk_mul_f32 v[80:81], v[80:81], v[84:85]
	v_pk_mul_f32 v[82:83], v[82:83], v[86:87]
	v_cvt_pk_bf16_f32 v84, v88, v89
	v_cvt_pk_bf16_f32 v85, v90, v91
	v_cvt_pk_bf16_f32 v80, v80, v81
	v_cvt_pk_bf16_f32 v81, v82, v83
	global_store_dwordx2 v[98:99], v[84:85], off
	global_store_dwordx2 v[98:99], v[80:81], off offset:128
	v_mad_i64_i32 v[82:83], s[24:25], v96, s39, v[146:147]
	v_lshl_add_u64 v[82:83], v[82:83], 0, v[150:151]
	s_waitcnt vmcnt(10)
	v_fmamk_f32 v80, v239, 0x3a000000, v158
	v_rsq_f32_e32 v80, v80
	s_nop 0
	v_pk_mul_f32 v[78:79], v[78:79], v[80:81] op_sel_hi:[1,0]
	v_pk_mul_f32 v[76:77], v[76:77], v[80:81] op_sel_hi:[1,0]
	v_pk_mul_f32 v[74:75], v[74:75], v[80:81] op_sel_hi:[1,0]
	v_pk_mul_f32 v[72:73], v[72:73], v[80:81] op_sel_hi:[1,0]
	v_pk_mul_f32 v[70:71], v[70:71], v[80:81] op_sel_hi:[1,0]
	v_pk_mul_f32 v[68:69], v[68:69], v[80:81] op_sel_hi:[1,0]
	v_pk_mul_f32 v[66:67], v[66:67], v[80:81] op_sel_hi:[1,0]
	v_pk_mul_f32 v[64:65], v[64:65], v[80:81] op_sel_hi:[1,0]
	v_mul_f32_e32 v80, 0xbfb8aa3b, v76
	v_mul_f32_e32 v81, 0xbfb8aa3b, v77
	v_mul_f32_e32 v84, 0xbfb8aa3b, v78
	v_mul_f32_e32 v85, 0xbfb8aa3b, v79
	v_mul_f32_e32 v86, 0xbfb8aa3b, v68
	v_mul_f32_e32 v87, 0xbfb8aa3b, v69
	v_mul_f32_e32 v88, 0xbfb8aa3b, v70
	v_mul_f32_e32 v89, 0xbfb8aa3b, v71
	v_exp_f32_e32 v80, v80
	v_exp_f32_e32 v81, v81
	v_exp_f32_e32 v84, v84
	v_exp_f32_e32 v85, v85
	v_exp_f32_e32 v86, v86
	v_exp_f32_e32 v87, v87
	v_exp_f32_e32 v88, v88
	v_exp_f32_e32 v89, v89
	v_add_f32_e32 v80, 1.0, v80
	v_add_f32_e32 v81, 1.0, v81
	v_add_f32_e32 v84, 1.0, v84
	v_add_f32_e32 v85, 1.0, v85
	v_add_f32_e32 v86, 1.0, v86
	v_add_f32_e32 v87, 1.0, v87
	v_add_f32_e32 v88, 1.0, v88
	v_add_f32_e32 v89, 1.0, v89
	v_rcp_f32_e32 v80, v80
	v_rcp_f32_e32 v81, v81
	v_rcp_f32_e32 v84, v84
	v_rcp_f32_e32 v85, v85
	v_rcp_f32_e32 v86, v86
	v_rcp_f32_e32 v87, v87
	v_rcp_f32_e32 v88, v88
	v_rcp_f32_e32 v89, v89
	v_pk_mul_f32 v[76:77], v[76:77], v[80:81]
	v_pk_mul_f32 v[78:79], v[78:79], v[84:85]
	v_pk_mul_f32 v[68:69], v[68:69], v[86:87]
	v_pk_mul_f32 v[70:71], v[70:71], v[88:89]
	v_pk_mul_f32 v[72:73], v[72:73], v[76:77]
	v_pk_mul_f32 v[74:75], v[74:75], v[78:79]
	v_pk_mul_f32 v[64:65], v[64:65], v[68:69]
	v_pk_mul_f32 v[66:67], v[66:67], v[70:71]
	v_cvt_pk_bf16_f32 v68, v72, v73
	v_cvt_pk_bf16_f32 v69, v74, v75
	v_cvt_pk_bf16_f32 v64, v64, v65
	v_cvt_pk_bf16_f32 v65, v66, v67
	global_store_dwordx2 v[82:83], v[68:69], off
	global_store_dwordx2 v[82:83], v[64:65], off offset:128
	v_add_u32_e32 v65, 0x80, v144
	v_mad_i64_i32 v[66:67], s[24:25], v65, s39, v[146:147]
	v_lshl_add_u64 v[66:67], v[66:67], 0, v[150:151]
	s_waitcnt vmcnt(11)
	v_fmamk_f32 v64, v240, 0x3a000000, v158
	v_rsq_f32_e32 v64, v64
	s_nop 0
	v_pk_mul_f32 v[62:63], v[62:63], v[64:65] op_sel_hi:[1,0]
	v_pk_mul_f32 v[60:61], v[60:61], v[64:65] op_sel_hi:[1,0]
	v_pk_mul_f32 v[58:59], v[58:59], v[64:65] op_sel_hi:[1,0]
	v_pk_mul_f32 v[56:57], v[56:57], v[64:65] op_sel_hi:[1,0]
	v_pk_mul_f32 v[54:55], v[54:55], v[64:65] op_sel_hi:[1,0]
	v_pk_mul_f32 v[52:53], v[52:53], v[64:65] op_sel_hi:[1,0]
	v_pk_mul_f32 v[50:51], v[50:51], v[64:65] op_sel_hi:[1,0]
	v_pk_mul_f32 v[48:49], v[48:49], v[64:65] op_sel_hi:[1,0]
	v_mul_f32_e32 v64, 0xbfb8aa3b, v60
	v_mul_f32_e32 v65, 0xbfb8aa3b, v61
	v_mul_f32_e32 v68, 0xbfb8aa3b, v62
	v_mul_f32_e32 v69, 0xbfb8aa3b, v63
	v_mul_f32_e32 v70, 0xbfb8aa3b, v52
	v_mul_f32_e32 v71, 0xbfb8aa3b, v53
	v_mul_f32_e32 v72, 0xbfb8aa3b, v54
	v_mul_f32_e32 v73, 0xbfb8aa3b, v55
	v_exp_f32_e32 v64, v64
	v_exp_f32_e32 v65, v65
	v_exp_f32_e32 v68, v68
	v_exp_f32_e32 v69, v69
	v_exp_f32_e32 v70, v70
	v_exp_f32_e32 v71, v71
	v_exp_f32_e32 v72, v72
	v_exp_f32_e32 v73, v73
	v_add_f32_e32 v64, 1.0, v64
	v_add_f32_e32 v65, 1.0, v65
	v_add_f32_e32 v68, 1.0, v68
	v_add_f32_e32 v69, 1.0, v69
	v_add_f32_e32 v70, 1.0, v70
	v_add_f32_e32 v71, 1.0, v71
	v_add_f32_e32 v72, 1.0, v72
	v_add_f32_e32 v73, 1.0, v73
	v_rcp_f32_e32 v64, v64
	v_rcp_f32_e32 v65, v65
	v_rcp_f32_e32 v68, v68
	v_rcp_f32_e32 v69, v69
	v_rcp_f32_e32 v70, v70
	v_rcp_f32_e32 v71, v71
	v_rcp_f32_e32 v72, v72
	v_rcp_f32_e32 v73, v73
	v_pk_mul_f32 v[60:61], v[60:61], v[64:65]
	v_pk_mul_f32 v[62:63], v[62:63], v[68:69]
	v_pk_mul_f32 v[52:53], v[52:53], v[70:71]
	v_pk_mul_f32 v[54:55], v[54:55], v[72:73]
	v_pk_mul_f32 v[56:57], v[56:57], v[60:61]
	v_pk_mul_f32 v[58:59], v[58:59], v[62:63]
	v_pk_mul_f32 v[48:49], v[48:49], v[52:53]
	v_pk_mul_f32 v[50:51], v[50:51], v[54:55]
	v_cvt_pk_bf16_f32 v52, v56, v57
	v_cvt_pk_bf16_f32 v53, v58, v59
	v_cvt_pk_bf16_f32 v48, v48, v49
	v_cvt_pk_bf16_f32 v49, v50, v51
	global_store_dwordx2 v[66:67], v[52:53], off
	global_store_dwordx2 v[66:67], v[48:49], off offset:128
	v_add_u32_e32 v49, 0x90, v144
	v_mad_i64_i32 v[50:51], s[24:25], v49, s39, v[146:147]
	v_lshl_add_u64 v[50:51], v[50:51], 0, v[150:151]
	s_waitcnt vmcnt(12)
; DI unsigned pk2(float lo, float hi) { const f32x2 v = {lo, hi}; const hwbf16x2 b = __builtin_convertvector(v, hwbf16x2); return __builtin_bit_cast(unsigned, b); }
; DI float frsq(float x) { return __builtin_amdgcn_rsqf(x); }
; DI float fsilu(float v) { return v * frcp(1.f + __expf(-v)); }
;     DI void operator()(const f32x4 (&acc)[2][2][4][2], const Unit& u, int wr, int wc, int fr, int fq) const {
;         const int row0 = u.pm * BM + wr * 64 + fr, col0 = u.pn * BM + wc * 32 + 8 * fq;
; #pragma unroll
;         for (int ai = 0; ai < 2; ++ai)
; #pragma unroll
;             for (int m = 0; m < 4; ++m) {
;                 const int row = row0 + ai * HALF + m * 16;
;                 float rs = 1.f, rowacc = 0.f;
;                 if (mode == EPI_STORE || mode == EPI_Q) { if (rscale) rs = rscale[row]; }
;                 if (mode == EPI_SWIGLU) rs = frsq(rowsq[row] * (1.0f / DM) + 1e-6f);
; #pragma unroll
;                 for (int bj = 0; bj < 2; ++bj) {
;     ...
;                     } else {
;                         v0 = v0 * rs; v1 = v1 * rs;
;                         u32x2 w; w.x = pk2(fsilu(v0[0]) * v1[0], fsilu(v0[1]) * v1[1]); w.y = pk2(fsilu(v0[2]) * v1[2], fsilu(v0[3]) * v1[3]);
;                         *(u32x2*)(O + (size_t)row * ldc + (col >> 1)) = w;
;                     }
	v_fmamk_f32 v48, v241, 0x3a000000, v158
	v_rsq_f32_e32 v48, v48
	s_nop 0
	v_pk_mul_f32 v[46:47], v[46:47], v[48:49] op_sel_hi:[1,0]
	v_pk_mul_f32 v[44:45], v[44:45], v[48:49] op_sel_hi:[1,0]
	v_pk_mul_f32 v[42:43], v[42:43], v[48:49] op_sel_hi:[1,0]
	v_pk_mul_f32 v[40:41], v[40:41], v[48:49] op_sel_hi:[1,0]
	v_pk_mul_f32 v[38:39], v[38:39], v[48:49] op_sel_hi:[1,0]
	v_pk_mul_f32 v[36:37], v[36:37], v[48:49] op_sel_hi:[1,0]
	v_pk_mul_f32 v[34:35], v[34:35], v[48:49] op_sel_hi:[1,0]
	v_pk_mul_f32 v[32:33], v[32:33], v[48:49] op_sel_hi:[1,0]
	v_mul_f32_e32 v48, 0xbfb8aa3b, v44
	v_mul_f32_e32 v49, 0xbfb8aa3b, v45
	v_mul_f32_e32 v52, 0xbfb8aa3b, v46
	v_mul_f32_e32 v53, 0xbfb8aa3b, v47
	v_mul_f32_e32 v54, 0xbfb8aa3b, v36
	v_mul_f32_e32 v55, 0xbfb8aa3b, v37
	v_mul_f32_e32 v56, 0xbfb8aa3b, v38
	v_mul_f32_e32 v57, 0xbfb8aa3b, v39
	v_exp_f32_e32 v48, v48
	v_exp_f32_e32 v49, v49
	v_exp_f32_e32 v52, v52
	v_exp_f32_e32 v53, v53
	v_exp_f32_e32 v54, v54
	v_exp_f32_e32 v55, v55
	v_exp_f32_e32 v56, v56
	v_exp_f32_e32 v57, v57
	v_add_f32_e32 v48, 1.0, v48
	v_add_f32_e32 v49, 1.0, v49
	v_add_f32_e32 v52, 1.0, v52
	v_add_f32_e32 v53, 1.0, v53
	v_add_f32_e32 v54, 1.0, v54
	v_add_f32_e32 v55, 1.0, v55
	v_add_f32_e32 v56, 1.0, v56
	v_add_f32_e32 v57, 1.0, v57
	v_rcp_f32_e32 v48, v48
	v_rcp_f32_e32 v49, v49
	v_rcp_f32_e32 v52, v52
	v_rcp_f32_e32 v53, v53
	v_rcp_f32_e32 v54, v54
	v_rcp_f32_e32 v55, v55
	v_rcp_f32_e32 v56, v56
	v_rcp_f32_e32 v57, v57
	v_pk_mul_f32 v[44:45], v[44:45], v[48:49]
	v_pk_mul_f32 v[46:47], v[46:47], v[52:53]
	v_pk_mul_f32 v[36:37], v[36:37], v[54:55]
	v_pk_mul_f32 v[38:39], v[38:39], v[56:57]
	v_pk_mul_f32 v[40:41], v[40:41], v[44:45]
	v_pk_mul_f32 v[42:43], v[42:43], v[46:47]
	v_pk_mul_f32 v[32:33], v[32:33], v[36:37]
	v_pk_mul_f32 v[34:35], v[34:35], v[38:39]
	v_cvt_pk_bf16_f32 v36, v40, v41
	v_cvt_pk_bf16_f32 v37, v42, v43
	v_cvt_pk_bf16_f32 v32, v32, v33
	v_cvt_pk_bf16_f32 v33, v34, v35
	global_store_dwordx2 v[50:51], v[36:37], off
	global_store_dwordx2 v[50:51], v[32:33], off offset:128
	v_add_u32_e32 v33, 0xa0, v144
	v_mad_i64_i32 v[34:35], s[24:25], v33, s39, v[146:147]
	v_lshl_add_u64 v[34:35], v[34:35], 0, v[150:151]
	s_waitcnt vmcnt(13)
	v_fmamk_f32 v32, v242, 0x3a000000, v158
	v_rsq_f32_e32 v32, v32
	s_nop 0
	v_pk_mul_f32 v[30:31], v[30:31], v[32:33] op_sel_hi:[1,0]
	v_pk_mul_f32 v[28:29], v[28:29], v[32:33] op_sel_hi:[1,0]
	v_pk_mul_f32 v[26:27], v[26:27], v[32:33] op_sel_hi:[1,0]
	v_pk_mul_f32 v[24:25], v[24:25], v[32:33] op_sel_hi:[1,0]
	v_pk_mul_f32 v[22:23], v[22:23], v[32:33] op_sel_hi:[1,0]
	v_pk_mul_f32 v[20:21], v[20:21], v[32:33] op_sel_hi:[1,0]
	v_pk_mul_f32 v[18:19], v[18:19], v[32:33] op_sel_hi:[1,0]
	v_pk_mul_f32 v[16:17], v[16:17], v[32:33] op_sel_hi:[1,0]
	v_mul_f32_e32 v32, 0xbfb8aa3b, v28
	v_mul_f32_e32 v33, 0xbfb8aa3b, v29
	v_mul_f32_e32 v36, 0xbfb8aa3b, v30
	v_mul_f32_e32 v37, 0xbfb8aa3b, v31
	v_mul_f32_e32 v38, 0xbfb8aa3b, v20
	v_mul_f32_e32 v39, 0xbfb8aa3b, v21
	v_mul_f32_e32 v40, 0xbfb8aa3b, v22
	v_mul_f32_e32 v41, 0xbfb8aa3b, v23
	v_exp_f32_e32 v32, v32
	v_exp_f32_e32 v33, v33
	v_exp_f32_e32 v36, v36
	v_exp_f32_e32 v37, v37
	v_exp_f32_e32 v38, v38
	v_exp_f32_e32 v39, v39
	v_exp_f32_e32 v40, v40
	v_exp_f32_e32 v41, v41
	v_add_f32_e32 v32, 1.0, v32
	v_add_f32_e32 v33, 1.0, v33
	v_add_f32_e32 v36, 1.0, v36
	v_add_f32_e32 v37, 1.0, v37
	v_add_f32_e32 v38, 1.0, v38
	v_add_f32_e32 v39, 1.0, v39
	v_add_f32_e32 v40, 1.0, v40
	v_add_f32_e32 v41, 1.0, v41
	v_rcp_f32_e32 v32, v32
	v_rcp_f32_e32 v33, v33
	v_rcp_f32_e32 v36, v36
	v_rcp_f32_e32 v37, v37
	v_rcp_f32_e32 v38, v38
	v_rcp_f32_e32 v39, v39
	v_rcp_f32_e32 v40, v40
	v_rcp_f32_e32 v41, v41
	v_pk_mul_f32 v[28:29], v[28:29], v[32:33]
	v_pk_mul_f32 v[30:31], v[30:31], v[36:37]
	v_pk_mul_f32 v[20:21], v[20:21], v[38:39]
	v_pk_mul_f32 v[22:23], v[22:23], v[40:41]
	v_pk_mul_f32 v[24:25], v[24:25], v[28:29]
	v_pk_mul_f32 v[26:27], v[26:27], v[30:31]
	v_pk_mul_f32 v[16:17], v[16:17], v[20:21]
	v_pk_mul_f32 v[18:19], v[18:19], v[22:23]
	v_cvt_pk_bf16_f32 v20, v24, v25
	v_cvt_pk_bf16_f32 v21, v26, v27
	v_cvt_pk_bf16_f32 v16, v16, v17
	v_cvt_pk_bf16_f32 v17, v18, v19
	global_store_dwordx2 v[34:35], v[20:21], off
	global_store_dwordx2 v[34:35], v[16:17], off offset:128
	v_add_u32_e32 v17, 0xb0, v144
	v_mad_i64_i32 v[18:19], s[24:25], v17, s39, v[146:147]
	v_lshl_add_u64 v[18:19], v[18:19], 0, v[150:151]
	s_waitcnt vmcnt(14)
	v_fmamk_f32 v16, v243, 0x3a000000, v158
	v_rsq_f32_e32 v16, v16
	s_nop 0
	v_pk_mul_f32 v[14:15], v[14:15], v[16:17] op_sel_hi:[1,0]
	v_pk_mul_f32 v[12:13], v[12:13], v[16:17] op_sel_hi:[1,0]
	v_pk_mul_f32 v[10:11], v[10:11], v[16:17] op_sel_hi:[1,0]
	v_pk_mul_f32 v[8:9], v[8:9], v[16:17] op_sel_hi:[1,0]
	v_pk_mul_f32 v[6:7], v[6:7], v[16:17] op_sel_hi:[1,0]
	v_pk_mul_f32 v[4:5], v[4:5], v[16:17] op_sel_hi:[1,0]
	v_pk_mul_f32 v[2:3], v[2:3], v[16:17] op_sel_hi:[1,0]
	v_pk_mul_f32 v[0:1], v[0:1], v[16:17] op_sel_hi:[1,0]
	v_mul_f32_e32 v16, 0xbfb8aa3b, v12
	v_mul_f32_e32 v17, 0xbfb8aa3b, v13
	v_mul_f32_e32 v20, 0xbfb8aa3b, v14
	v_mul_f32_e32 v21, 0xbfb8aa3b, v15
	v_mul_f32_e32 v22, 0xbfb8aa3b, v4
	v_mul_f32_e32 v23, 0xbfb8aa3b, v5
	v_mul_f32_e32 v24, 0xbfb8aa3b, v6
	v_mul_f32_e32 v25, 0xbfb8aa3b, v7
	v_exp_f32_e32 v16, v16
	v_exp_f32_e32 v17, v17
	v_exp_f32_e32 v20, v20
	v_exp_f32_e32 v21, v21
	v_exp_f32_e32 v22, v22
	v_exp_f32_e32 v23, v23
	v_exp_f32_e32 v24, v24
	v_exp_f32_e32 v25, v25
	v_add_f32_e32 v16, 1.0, v16
	v_add_f32_e32 v17, 1.0, v17
	v_add_f32_e32 v20, 1.0, v20
	v_add_f32_e32 v21, 1.0, v21
	v_add_f32_e32 v22, 1.0, v22
	v_add_f32_e32 v23, 1.0, v23
	v_add_f32_e32 v24, 1.0, v24
	v_add_f32_e32 v25, 1.0, v25
	v_rcp_f32_e32 v16, v16
	v_rcp_f32_e32 v17, v17
	v_rcp_f32_e32 v20, v20
	v_rcp_f32_e32 v21, v21
	v_rcp_f32_e32 v22, v22
	v_rcp_f32_e32 v23, v23
	v_rcp_f32_e32 v24, v24
	v_rcp_f32_e32 v25, v25
	v_pk_mul_f32 v[12:13], v[12:13], v[16:17]
	v_pk_mul_f32 v[14:15], v[14:15], v[20:21]
	v_pk_mul_f32 v[4:5], v[4:5], v[22:23]
	v_pk_mul_f32 v[6:7], v[6:7], v[24:25]
	v_pk_mul_f32 v[8:9], v[8:9], v[12:13]
	v_pk_mul_f32 v[10:11], v[10:11], v[14:15]
	v_pk_mul_f32 v[0:1], v[0:1], v[4:5]
	v_pk_mul_f32 v[2:3], v[2:3], v[6:7]
	v_cvt_pk_bf16_f32 v4, v8, v9
	v_cvt_pk_bf16_f32 v5, v10, v11
	v_cvt_pk_bf16_f32 v0, v0, v1
	v_cvt_pk_bf16_f32 v1, v2, v3
	global_store_dwordx2 v[18:19], v[4:5], off
	global_store_dwordx2 v[18:19], v[0:1], off offset:128
	s_cbranch_vccnz .LBB0_1016
	s_andn2_b64 vcc, exec, s[6:7]
	s_cbranch_vccnz .LBB0_1015
	s_barrier
	s_branch .LBB0_1015

; __global__ void __launch_bounds__(NTHREADS, 2) fwd_megakernel(Params p) {
	.amdhsa_kernel _Z14fwd_megakernel6Params
		.amdhsa_group_segment_fixed_size 0
		.amdhsa_private_segment_fixed_size 0
		.amdhsa_kernarg_size 432
		.amdhsa_user_sgpr_count 2
		.amdhsa_user_sgpr_dispatch_ptr 0
		.amdhsa_user_sgpr_queue_ptr 0
		.amdhsa_user_sgpr_kernarg_segment_ptr 1
		.amdhsa_user_sgpr_dispatch_id 0
		.amdhsa_user_sgpr_kernarg_preload_length 0
		.amdhsa_user_sgpr_kernarg_preload_offset 0
		.amdhsa_user_sgpr_private_segment_size 0
		.amdhsa_uses_dynamic_stack 0
		.amdhsa_enable_private_segment 0
		.amdhsa_system_sgpr_workgroup_id_x 1
		.amdhsa_system_sgpr_workgroup_id_y 0
		.amdhsa_system_sgpr_workgroup_id_z 0
		.amdhsa_system_sgpr_workgroup_info 0
		.amdhsa_system_vgpr_workitem_id 2
		.amdhsa_next_free_vgpr 248
		.amdhsa_next_free_sgpr 98
		.amdhsa_accum_offset 248
		.amdhsa_reserve_vcc 1
		.amdhsa_float_round_mode_32 0
		.amdhsa_float_round_mode_16_64 0
		.amdhsa_float_denorm_mode_32 3
		.amdhsa_float_denorm_mode_16_64 3
		.amdhsa_dx10_clamp 1
		.amdhsa_ieee_mode 1
		.amdhsa_fp16_overflow 0
		.amdhsa_tg_split 0
		.amdhsa_exception_fp_ieee_invalid_op 0
		.amdhsa_exception_fp_denorm_src 0
		.amdhsa_exception_fp_ieee_div_zero 0
		.amdhsa_exception_fp_ieee_overflow 0
		.amdhsa_exception_fp_ieee_underflow 0
		.amdhsa_exception_fp_ieee_inexact 0
		.amdhsa_exception_int_div_zero 0
	.end_amdhsa_kernel

; __global__ void __launch_bounds__(NTHREADS, 2) fwd_megakernel(Params p) {
amdhsa.kernels:
  - .agpr_count:     0
    .args:
      - .offset:         0
        .size:           176
        .value_kind:     by_value
      - .offset:         176
        .size:           4
        .value_kind:     hidden_block_count_x
      - .offset:         180
        .size:           4
        .value_kind:     hidden_block_count_y
      - .offset:         184
        .size:           4
        .value_kind:     hidden_block_count_z
      - .offset:         188
        .size:           2
        .value_kind:     hidden_group_size_x
      - .offset:         190
        .size:           2
        .value_kind:     hidden_group_size_y
      - .offset:         192
        .size:           2
        .value_kind:     hidden_group_size_z
      - .offset:         194
        .size:           2
        .value_kind:     hidden_remainder_x
      - .offset:         196
        .size:           2
        .value_kind:     hidden_remainder_y
      - .offset:         198
        .size:           2
        .value_kind:     hidden_remainder_z
      - .offset:         216
        .size:           8
        .value_kind:     hidden_global_offset_x
      - .offset:         224
        .size:           8
        .value_kind:     hidden_global_offset_y
      - .offset:         232
        .size:           8
        .value_kind:     hidden_global_offset_z
      - .offset:         240
        .size:           2
        .value_kind:     hidden_grid_dims
      - .offset:         264
        .size:           8
        .value_kind:     hidden_multigrid_sync_arg
      - .offset:         296
        .size:           4
        .value_kind:     hidden_dynamic_lds_size
    .group_segment_fixed_size: 0
    .kernarg_segment_align: 8
    .kernarg_segment_size: 432
    .language:       OpenCL C
    .language_version:
      - 2
      - 0
    .max_flat_workgroup_size: 512
    .name:           _Z14fwd_megakernel6Params
    .private_segment_fixed_size: 0
    .sgpr_count:     104
    .sgpr_spill_count: 36
    .symbol:         _Z14fwd_megakernel6Params.kd
    .uniform_work_group_size: 1
    .uses_dynamic_stack: false
    .vgpr_count:     248
    .vgpr_spill_count: 0
    .wavefront_size: 64
